# R2/R3 fast bodies: software pipeline across iterations - next iteration's row A x/Y loads and modulation chunk DMAs (other LDS buffer) are issued in the middle of the current iteration
# speedup vs baseline: 1.0067x; 1.0067x over previous
; __device__ __forceinline__ float bflo(unsigned w) { return __uint_as_float(w << 16); }
; __device__ __forceinline__ void row_pass(const RowPass& R, int gw, int ngw, int lane) {
;     constexpr int NR = 2;
;     for (int row0 = gw; row0 < M; row0 += NR * ngw) {
;         f32x4 v[NR][4]; u32x2 yw[NR][4]; bool act[NR]; float* xrow[NR]; int bbs[NR];
; #pragma unroll
;         for (int k = 0; k < NR; ++k) {
;             const int row = row0 + k * ngw;
;             const int rowc = row < M ? row : row0;
;             const int b = rowc / RPB, i = rowc - b * RPB; const bool isctx = i < CTXL;
;             act[k] = (row < M) && !(isctx && R.skip_ctx);
;             bbs[k] = isctx ? 8 : b;
;             xrow[k] = isctx ? R.xc + ((size_t)b * CTXL + i) * DM : R.out + ((size_t)b * SEQ + (i - CTXL)) * DM;
;             const float* src = R.init ? (isctx ? R.ctx_in + ((size_t)b * CTXL + i) * DM : R.x_in + ((size_t)b * SEQ + (i - CTXL)) * DM) : xrow[k];
;             if (act[k]) {
; #pragma unroll
;                 for (int j = 0; j < 4; ++j) v[k][j] = __builtin_nontemporal_load((const f32x4*)(src + lane * 4 + 256 * j));
;                 if (R.update) { const bf16* yr = R.Y + (size_t)rowc * DM;
; #pragma unroll
;                     for (int j = 0; j < 4; ++j) yw[k][j] = __builtin_nontemporal_load((const u32x2*)(yr + lane * 4 + 256 * j)); }
;             }
;         }
; #pragma unroll
;         for (int k = 0; k < NR; ++k) {
;             if (!act[k]) continue;
;             const int row = row0 + k * ngw, bb = bbs[k];
;             if (R.update) {
;                 f32x4 y[4]; float ss = 0.f;
; #pragma unroll
;                 for (int j = 0; j < 4; ++j) { const u32x2 w = yw[k][j]; y[j] = (f32x4){bflo(w.x), bfhi(w.x), bflo(w.y), bfhi(w.y)};
;                     ss += (y[j][0] * y[j][0] + y[j][1] * y[j][1]) + (y[j][2] * y[j][2] + y[j][3] * y[j][3]); }
;                 const float rstd = __builtin_amdgcn_rsqf(wave_sum(ss) * (1.0f / DM) + EPS);
;                 const float* gate = R.mod + ((size_t)(R.lg * 9 + bb) * NMOD + R.gi) * DM;
; #pragma unroll
;                 for (int j = 0; j < 4; ++j) { const f32x4 g = *(const f32x4*)(gate + lane * 4 + 256 * j), gp = *(const f32x4*)(R.gpost + lane * 4 + 256 * j);
;                     v[k][j] = v[k][j] + g * (y[j] * rstd * gp); }
.LBB0_128:
	s_cmp_gt_i32 s84, 2
	s_mov_b64 s[4:5], -1
	s_cbranch_scc0 .LBB0_141
	s_cmp_gt_i32 s36, 0x87ff
	s_cbranch_scc1 .LBB0_140
	s_sub_i32 s3, s57, 30
	s_load_dwordx2 s[4:5], s[0:1], 0xa0
	s_load_dwordx4 s[8:11], s[0:1], 0x38
	s_cmp_lt_u32 s3, -7
	s_cselect_b64 s[62:63], -1, 0
	s_lshl_b32 s6, s12, 10
	s_ashr_i32 s7, s6, 31
	s_lshl_b64 s[6:7], s[6:7], 2
	s_waitcnt lgkmcnt(0)
	s_add_u32 s10, s10, s6
	s_addc_u32 s11, s11, s7
	s_add_u32 s6, s8, s6
	s_addc_u32 s7, s9, s7
	s_waitcnt vmcnt(0)
	v_lshlrev_b32_e32 v0, 4, v216
	v_mov_b32_e32 v1, v161
	s_ashr_i32 s37, s36, 31
	v_lshl_add_u64 v[42:43], s[6:7], 0, v[0:1]
	s_lshl_b64 s[6:7], s[36:37], 11
	s_add_u32 s6, s28, s6
	v_lshlrev_b32_e32 v160, 3, v216
	s_addc_u32 s7, s29, s7
	v_lshl_add_u64 v[44:45], s[10:11], 0, v[0:1]
	v_lshl_add_u64 v[0:1], s[6:7], 0, v[160:161]
	s_mov_b64 s[6:7], 0xa7fa600
	v_lshlrev_b32_e32 v36, 2, v216
	v_lshl_add_u64 v[38:39], s[20:21], 0, v[160:161]
	v_lshl_add_u64 v[40:41], s[60:61], 0, v[160:161]
	s_mul_i32 s3, s12, 9
	v_lshl_add_u64 v[46:47], v[0:1], 0, s[6:7]
	s_mov_b32 s93, 0
	s_mov_b32 s99, 0
	global_load_dwordx4 v[218:221], v[42:43], off
	global_load_dwordx4 v[222:225], v[42:43], off offset:1024
	global_load_dwordx4 v[226:229], v[42:43], off offset:2048
	global_load_dwordx4 v[230:233], v[42:43], off offset:3072
	global_load_dwordx4 v[234:237], v[44:45], off
	global_load_dwordx4 v[238:241], v[44:45], off offset:1024
	global_load_dwordx4 v[242:245], v[44:45], off offset:2048
	global_load_dwordx4 v[246:249], v[44:45], off offset:3072
	s_mov_b32 s13, s36
	s_branch .LBB0_132

;     __device__ __forceinline__ void init(int N, int G, int c, int latent_only) { lat = latent_only; b.init(latent_only ? NB * SEQ : M, N, G, c); }
;     __device__ __forceinline__ void init(int c_, unsigned* cnt_) { lat.init(NB * SEQ, FF2, 1, 0); c = c_; cnt = cnt_; }
; __device__ __forceinline__ void row_pass(const RowPass& R, int gw, int ngw, int lane) {
;     ...
;     for (int row0 = gw; row0 < M; row0 += NR * ngw) {
;         f32x4 v[NR][4]; u32x2 yw[NR][4]; bool act[NR]; float* xrow[NR]; int bbs[NR];
; #pragma unroll
;         for (int k = 0; k < NR; ++k) {
;             const int row = row0 + k * ngw;
;             const int rowc = row < M ? row : row0;
;             const int b = rowc / RPB, i = rowc - b * RPB; const bool isctx = i < CTXL;
;             act[k] = (row < M) && !(isctx && R.skip_ctx);
;             bbs[k] = isctx ? 8 : b;
;             xrow[k] = isctx ? R.xc + ((size_t)b * CTXL + i) * DM : R.out + ((size_t)b * SEQ + (i - CTXL)) * DM;
;             const float* src = R.init ? (isctx ? R.ctx_in + ((size_t)b * CTXL + i) * DM : R.x_in + ((size_t)b * SEQ + (i - CTXL)) * DM) : xrow[k];
;             if (act[k]) {
; #pragma unroll
;                 for (int j = 0; j < 4; ++j) v[k][j] = __builtin_nontemporal_load((const f32x4*)(src + lane * 4 + 256 * j));
;                 if (R.update) { const bf16* yr = R.Y + (size_t)rowc * DM;
; #pragma unroll
;                     for (int j = 0; j < 4; ++j) yw[k][j] = __builtin_nontemporal_load((const u32x2*)(yr + lane * 4 + 256 * j)); }
;             }
.LBB0_132:
	s_mul_hi_i32 s6, s13, 0x78787879
	s_lshr_b32 s7, s6, 31
	s_ashr_i32 s6, s6, 11
	s_add_i32 s6, s6, s7
	s_mul_i32 s7, s6, 0xffffef00
	s_add_i32 s7, s13, s7
	s_cmpk_gt_i32 s7, 0xff
	s_cselect_b64 s[50:51], -1, 0
	s_add_i32 s8, s44, s13
	s_cmp_lt_i32 s8, 0x8800
	s_cbranch_scc0 .Lr2_slow
	s_mul_hi_i32 s9, s8, 0x78787879
	s_lshr_b32 s25, s9, 31
	s_ashr_i32 s9, s9, 11
	s_add_i32 s9, s9, s25
	s_mul_i32 s25, s9, 0xffffef00
	s_add_i32 s25, s8, s25
	s_cmpk_gt_i32 s25, 0xff
	s_cselect_b64 s[52:53], -1, 0
	s_and_b64 s[46:47], s[50:51], s[52:53]
	s_or_b64 s[46:47], s[46:47], s[62:63]
	s_cmp_lg_u64 s[46:47], 0
	s_cbranch_scc0 .Lr2_slow
	v_lshlrev_b32_e32 v160, 2, v36
	s_add_i32 s72, s7, 0xffffff00
	s_cmp_lg_u64 s[50:51], 0
	s_cselect_b32 s27, s4, s49
	s_cselect_b32 s32, s5, s55
	s_cselect_b32 s37, 24, 20
	s_cselect_b32 s72, s72, s7
	s_cselect_b32 s85, s6, 8
	s_mov_b32 s40, s6
	s_mov_b32 s41, 0
	s_lshl_b64 s[40:41], s[40:41], s37
	s_add_u32 s40, s27, s40
	s_addc_u32 s41, s32, s41
	s_lshl_b32 s72, s72, 12
	s_add_u32 s40, s40, s72
	s_addc_u32 s41, s41, 0
	s_add_i32 s27, s85, s3
	s_mul_hi_i32 s32, s27, 0x6000
	s_mulk_i32 s27, 0x6000
	s_add_u32 s66, s34, s27
	s_addc_u32 s67, s35, s32
	s_add_u32 s66, s66, 0x2000
	s_addc_u32 s67, s67, 0
	s_add_i32 s27, s85, s3
	s_mul_hi_i32 s32, s27, 0x6000
	s_mulk_i32 s27, 0x6000
	s_add_u32 s38, s34, s27
	s_addc_u32 s39, s35, s32
	s_add_u32 s38, s38, 0x3000
	s_addc_u32 s39, s39, 0
	s_add_u32 s46, s38, 0x1000
	s_addc_u32 s47, s39, 0
	s_mov_b32 s6, s8
	s_ashr_i32 s7, s8, 31
	s_lshl_b64 s[6:7], s[6:7], 11
	v_lshl_add_u64 v[250:251], v[38:39], 0, s[6:7]
	v_lshl_add_u64 v[252:253], v[40:41], 0, s[6:7]
	s_mov_b64 s[6:7], s[52:53]
	s_add_i32 s72, s25, 0xffffff00
	s_cmp_lg_u64 s[6:7], 0
	s_cselect_b32 s27, s4, s49
	s_cselect_b32 s32, s5, s55
	s_cselect_b32 s37, 24, 20
	s_cselect_b32 s72, s72, s25
	s_cselect_b32 s85, s9, 8
	s_mov_b32 s64, s9
	s_mov_b32 s65, 0
	s_lshl_b64 s[64:65], s[64:65], s37
	s_add_u32 s64, s27, s64
	s_addc_u32 s65, s32, s65
	s_lshl_b32 s72, s72, 12
	s_add_u32 s64, s64, s72
	s_addc_u32 s65, s65, 0
	s_add_i32 s27, s85, s3
	s_mul_hi_i32 s32, s27, 0x6000
	s_mulk_i32 s27, 0x6000
	s_add_u32 s10, s34, s27
	s_addc_u32 s11, s35, s32
	s_add_u32 s10, s10, 0x2000
	s_addc_u32 s11, s11, 0
	s_add_i32 s27, s85, s3
	s_mul_hi_i32 s32, s27, 0x6000
	s_mulk_i32 s27, 0x6000
	s_add_u32 s50, s34, s27
	s_addc_u32 s51, s35, s32
	s_add_u32 s50, s50, 0x3000
	s_addc_u32 s51, s51, 0
	s_add_u32 s52, s50, 0x1000
	s_addc_u32 s53, s51, 0
	s_cmp_lg_u32 s99, 0
	s_cbranch_scc1 .Lr2_slow_pf
	global_load_dwordx4 v[12:15], v160, s[40:41] nt
	global_load_dwordx4 v[8:11], v160, s[40:41] offset:1024 nt
	global_load_dwordx4 v[4:7], v160, s[40:41] offset:2048 nt
	global_load_dwordx4 v[0:3], v160, s[40:41] offset:3072 nt
	global_load_dwordx2 v[54:55], v[46:47], off offset:-1536 nt
	global_load_dwordx2 v[52:53], v[46:47], off offset:-1024 nt
	global_load_dwordx2 v[50:51], v[46:47], off offset:-512 nt
	global_load_dwordx2 v[48:49], v[46:47], off nt
	s_and_b32 s72, s13, 7
	s_and_b32 s85, s72, 3
	s_lshl_b32 s85, s85, 10
	s_lshl_b32 s37, s72, 10
	s_add_i32 s37, s37, s93
	s_cmp_lt_u32 s72, 4
	s_cselect_b32 s6, s66, s38
	s_cselect_b32 s7, s67, s39
	s_cselect_b32 s8, s46, s10
	s_cselect_b32 s9, s47, s11
	s_cselect_b32 s26, s50, s52
	s_cselect_b32 s27, s51, s53
	s_add_u32 s6, s6, s85
	s_addc_u32 s7, s7, 0
	s_add_u32 s8, s8, s85
	s_addc_u32 s9, s9, 0
	s_add_u32 s26, s26, s85
	s_addc_u32 s27, s27, 0
	s_mov_b32 m0, s37
	s_nop 0
	global_load_lds_dwordx4 v160, s[6:7]
	s_add_i32 s37, s37, 0x2000
	s_mov_b32 m0, s37
	s_nop 0
	global_load_lds_dwordx4 v160, s[8:9]
	s_add_i32 s37, s37, 0x2000
	s_mov_b32 m0, s37
	s_nop 0
	global_load_lds_dwordx4 v160, s[26:27]
	global_load_dwordx4 v[16:19], v160, s[64:65] nt
	global_load_dwordx4 v[20:23], v160, s[64:65] offset:1024 nt
	global_load_dwordx4 v[24:27], v160, s[64:65] offset:2048 nt
	global_load_dwordx4 v[28:31], v160, s[64:65] offset:3072 nt
	global_load_dwordx2 v[62:63], v[250:251], off nt
	global_load_dwordx2 v[60:61], v[250:251], off offset:512 nt
	global_load_dwordx2 v[58:59], v[250:251], off offset:1024 nt
	global_load_dwordx2 v[56:57], v[250:251], off offset:1536 nt
	s_waitcnt vmcnt(8)
	s_branch .Lr2_slow_proc
.Lr2_slow_pf:
	global_load_dwordx4 v[16:19], v160, s[64:65] nt
	global_load_dwordx4 v[20:23], v160, s[64:65] offset:1024 nt
	global_load_dwordx4 v[24:27], v160, s[64:65] offset:2048 nt
	global_load_dwordx4 v[28:31], v160, s[64:65] offset:3072 nt
	global_load_dwordx2 v[62:63], v[250:251], off nt
	global_load_dwordx2 v[60:61], v[250:251], off offset:512 nt
	global_load_dwordx2 v[58:59], v[250:251], off offset:1024 nt
	global_load_dwordx2 v[56:57], v[250:251], off offset:1536 nt
	s_waitcnt vmcnt(16)
; __device__ __forceinline__ float bflo(unsigned w) { return __uint_as_float(w << 16); }
; __device__ __forceinline__ float bfhi(unsigned w) { return __uint_as_float(w & 0xffff0000u); }
;     __device__ __forceinline__ void init(int N, int G, int c, int latent_only) { lat = latent_only; b.init(latent_only ? NB * SEQ : M, N, G, c); }
;     __device__ __forceinline__ void init(int c_, unsigned* cnt_) { lat.init(NB * SEQ, FF2, 1, 0); c = c_; cnt = cnt_; }
; __device__ __forceinline__ void row_pass(const RowPass& R, int gw, int ngw, int lane) {
;     ...
;             if (R.update) {
;                 f32x4 y[4]; float ss = 0.f;
; #pragma unroll
;                 for (int j = 0; j < 4; ++j) { const u32x2 w = yw[k][j]; y[j] = (f32x4){bflo(w.x), bfhi(w.x), bflo(w.y), bfhi(w.y)};
;                     ss += (y[j][0] * y[j][0] + y[j][1] * y[j][1]) + (y[j][2] * y[j][2] + y[j][3] * y[j][3]); }
;                 const float rstd = __builtin_amdgcn_rsqf(wave_sum(ss) * (1.0f / DM) + EPS);
;                 const float* gate = R.mod + ((size_t)(R.lg * 9 + bb) * NMOD + R.gi) * DM;
; #pragma unroll
;                 for (int j = 0; j < 4; ++j) { const f32x4 g = *(const f32x4*)(gate + lane * 4 + 256 * j), gp = *(const f32x4*)(R.gpost + lane * 4 + 256 * j);
;                     v[k][j] = v[k][j] + g * (y[j] * rstd * gp); }
;             }
;             if (R.init || R.update) {
; #pragma unroll
;                 for (int j = 0; j < 4; ++j) __builtin_nontemporal_store(v[k][j], (f32x4*)(xrow[k] + lane * 4 + 256 * j));
.Lr2_slow_proc:
	s_barrier
	v_add_u32_e32 v37, s93, v160
	ds_read_b128 v[64:67], v37
	ds_read_b128 v[68:71], v37 offset:1024
	ds_read_b128 v[72:75], v37 offset:2048
	ds_read_b128 v[76:79], v37 offset:3072
	ds_read_b128 v[80:83], v37 offset:4096
	ds_read_b128 v[84:87], v37 offset:5120
	ds_read_b128 v[88:91], v37 offset:6144
	ds_read_b128 v[92:95], v37 offset:7168
	ds_read_b128 v[172:175], v37 offset:8192
	ds_read_b128 v[176:179], v37 offset:9216
	ds_read_b128 v[180:183], v37 offset:10240
	ds_read_b128 v[184:187], v37 offset:11264
	v_lshlrev_b32_e32 v32, 16, v54
	v_and_b32_e32 v33, 0xffff0000, v54
	v_lshlrev_b32_e32 v34, 16, v55
	v_and_b32_e32 v35, 0xffff0000, v55
	v_pk_mul_f32 v[166:167], v[32:33], v[32:33]
	v_pk_mul_f32 v[168:169], v[34:35], v[34:35]
	v_lshlrev_b32_e32 v32, 16, v52
	v_and_b32_e32 v33, 0xffff0000, v52
	v_lshlrev_b32_e32 v34, 16, v53
	v_and_b32_e32 v35, 0xffff0000, v53
	v_pk_fma_f32 v[166:167], v[32:33], v[32:33], v[166:167]
	v_pk_fma_f32 v[168:169], v[34:35], v[34:35], v[168:169]
	v_lshlrev_b32_e32 v32, 16, v50
	v_and_b32_e32 v33, 0xffff0000, v50
	v_lshlrev_b32_e32 v34, 16, v51
	v_and_b32_e32 v35, 0xffff0000, v51
	v_pk_fma_f32 v[166:167], v[32:33], v[32:33], v[166:167]
	v_pk_fma_f32 v[168:169], v[34:35], v[34:35], v[168:169]
	v_lshlrev_b32_e32 v32, 16, v48
	v_and_b32_e32 v33, 0xffff0000, v48
	v_lshlrev_b32_e32 v34, 16, v49
	v_and_b32_e32 v35, 0xffff0000, v49
	v_pk_fma_f32 v[166:167], v[32:33], v[32:33], v[166:167]
	v_pk_fma_f32 v[168:169], v[34:35], v[34:35], v[168:169]
	v_pk_add_f32 v[166:167], v[166:167], v[168:169]
	s_nop 0
	v_add_f32_e32 v164, v166, v167
	v_mov_b32_e32 v165, v164
	s_nop 1
	v_permlane32_swap_b32_e32 v165, v164
	v_add_f32_e32 v164, v164, v165
	v_mov_b32_e32 v165, v164
	s_nop 1
	v_permlane16_swap_b32_e32 v165, v164
	v_add_f32_e32 v164, v164, v165
	s_nop 1
	v_add_f32_dpp v164, v164, v164 row_ror:8 row_mask:0xf bank_mask:0xf
	s_nop 1
	v_add_f32_dpp v164, v164, v164 row_ror:4 row_mask:0xf bank_mask:0xf
	s_nop 1
	v_add_f32_dpp v164, v164, v164 row_ror:2 row_mask:0xf bank_mask:0xf
	s_nop 1
	v_add_f32_dpp v164, v164, v164 row_ror:1 row_mask:0xf bank_mask:0xf
	s_nop 0
	v_fmamk_f32 v164, v164, 0x3a800000, v200
	v_rsq_f32_e32 v164, v164
	v_lshlrev_b32_e32 v32, 16, v54
	v_and_b32_e32 v33, 0xffff0000, v54
	v_lshlrev_b32_e32 v34, 16, v55
	v_and_b32_e32 v35, 0xffff0000, v55
	v_pk_mul_f32 v[32:33], v[32:33], v[164:165] op_sel_hi:[1,0]
	v_pk_mul_f32 v[34:35], v[34:35], v[164:165] op_sel_hi:[1,0]
	v_pk_mul_f32 v[32:33], v[218:219], v[32:33]
	v_pk_mul_f32 v[34:35], v[220:221], v[34:35]
	s_waitcnt lgkmcnt(11)
	v_pk_fma_f32 v[12:13], v[64:65], v[32:33], v[12:13]
	v_pk_fma_f32 v[14:15], v[66:67], v[34:35], v[14:15]
	global_store_dwordx4 v160, v[12:15], s[40:41] nt
	v_lshlrev_b32_e32 v32, 16, v52
	v_and_b32_e32 v33, 0xffff0000, v52
	v_lshlrev_b32_e32 v34, 16, v53
	v_and_b32_e32 v35, 0xffff0000, v53
	v_pk_mul_f32 v[32:33], v[32:33], v[164:165] op_sel_hi:[1,0]
	v_pk_mul_f32 v[34:35], v[34:35], v[164:165] op_sel_hi:[1,0]
	v_pk_mul_f32 v[32:33], v[222:223], v[32:33]
	v_pk_mul_f32 v[34:35], v[224:225], v[34:35]
	s_waitcnt lgkmcnt(10)
	v_pk_fma_f32 v[8:9], v[68:69], v[32:33], v[8:9]
	v_pk_fma_f32 v[10:11], v[70:71], v[34:35], v[10:11]
	global_store_dwordx4 v160, v[8:11], s[40:41] offset:1024 nt
	v_lshlrev_b32_e32 v32, 16, v50
	v_and_b32_e32 v33, 0xffff0000, v50
	v_lshlrev_b32_e32 v34, 16, v51
	v_and_b32_e32 v35, 0xffff0000, v51
	v_pk_mul_f32 v[32:33], v[32:33], v[164:165] op_sel_hi:[1,0]
	v_pk_mul_f32 v[34:35], v[34:35], v[164:165] op_sel_hi:[1,0]
	v_pk_mul_f32 v[32:33], v[226:227], v[32:33]
	v_pk_mul_f32 v[34:35], v[228:229], v[34:35]
	s_waitcnt lgkmcnt(9)
	v_pk_fma_f32 v[4:5], v[72:73], v[32:33], v[4:5]
	v_pk_fma_f32 v[6:7], v[74:75], v[34:35], v[6:7]
	global_store_dwordx4 v160, v[4:7], s[40:41] offset:2048 nt
	v_lshlrev_b32_e32 v32, 16, v48
	v_and_b32_e32 v33, 0xffff0000, v48
	v_lshlrev_b32_e32 v34, 16, v49
	v_and_b32_e32 v35, 0xffff0000, v49
	v_pk_mul_f32 v[32:33], v[32:33], v[164:165] op_sel_hi:[1,0]
	v_pk_mul_f32 v[34:35], v[34:35], v[164:165] op_sel_hi:[1,0]
	v_pk_mul_f32 v[32:33], v[230:231], v[32:33]
	v_pk_mul_f32 v[34:35], v[232:233], v[34:35]
	s_waitcnt lgkmcnt(8)
	v_pk_fma_f32 v[0:1], v[76:77], v[32:33], v[0:1]
	v_pk_fma_f32 v[2:3], v[78:79], v[34:35], v[2:3]
	global_store_dwordx4 v160, v[0:3], s[40:41] offset:3072 nt
	s_waitcnt lgkmcnt(0)
; __device__ __forceinline__ unsigned pk2(float lo, float hi) { return pg8::cvt_pk_bf16(lo, hi); }
; __device__ __forceinline__ void row_pass(const RowPass& R, int gw, int ngw, int lane) {
;     ...
;     for (int row0 = gw; row0 < M; row0 += NR * ngw) {
;         f32x4 v[NR][4]; u32x2 yw[NR][4]; bool act[NR]; float* xrow[NR]; int bbs[NR];
; #pragma unroll
;         for (int k = 0; k < NR; ++k) {
;             const int row = row0 + k * ngw;
;             const int rowc = row < M ? row : row0;
;             const int b = rowc / RPB, i = rowc - b * RPB; const bool isctx = i < CTXL;
;             act[k] = (row < M) && !(isctx && R.skip_ctx);
;             bbs[k] = isctx ? 8 : b;
;             xrow[k] = isctx ? R.xc + ((size_t)b * CTXL + i) * DM : R.out + ((size_t)b * SEQ + (i - CTXL)) * DM;
;             const float* src = R.init ? (isctx ? R.ctx_in + ((size_t)b * CTXL + i) * DM : R.x_in + ((size_t)b * SEQ + (i - CTXL)) * DM) : xrow[k];
;             if (act[k]) {
; #pragma unroll
;                 for (int j = 0; j < 4; ++j) v[k][j] = __builtin_nontemporal_load((const f32x4*)(src + lane * 4 + 256 * j));
;                 if (R.update) { const bf16* yr = R.Y + (size_t)rowc * DM;
; #pragma unroll
;                     for (int j = 0; j < 4; ++j) yw[k][j] = __builtin_nontemporal_load((const u32x2*)(yr + lane * 4 + 256 * j)); }
;             }
;     ...
;             if (R.norm_out) {
;                 float ss = 0.f;
; #pragma unroll
;                 for (int j = 0; j < 4; ++j) ss += (v[k][j][0] * v[k][j][0] + v[k][j][1] * v[k][j][1]) + (v[k][j][2] * v[k][j][2] + v[k][j][3] * v[k][j][3]);
;                 const float rstd = __builtin_amdgcn_rsqf(wave_sum(ss) * (1.0f / DM) + EPS);
;                 const float* shift = R.mod + ((size_t)(R.ln * 9 + bb) * NMOD + R.si) * DM; const float* scale = shift + DM;
;                 bf16* hr = R.H + (size_t)row * DM;
; #pragma unroll
;                 for (int j = 0; j < 4; ++j) { const f32x4 gp = *(const f32x4*)(R.gpre + lane * 4 + 256 * j), sh = *(const f32x4*)(shift + lane * 4 + 256 * j), sc = *(const f32x4*)(scale + lane * 4 + 256 * j);
;                     const f32x4 hv = (v[k][j] * rstd * gp) * (sc + 1.0f) + sh;
;                     u32x2 w; w.x = pk2(hv[0], hv[1]); w.y = pk2(hv[2], hv[3]); *(u32x2*)(hr + lane * 4 + 256 * j) = w; }
	ds_read_b128 v[188:191], v37 offset:12288
	ds_read_b128 v[192:195], v37 offset:13312
	ds_read_b128 v[196:199], v37 offset:14336
	ds_read_b128 v[96:99], v37 offset:15360
	ds_read_b128 v[64:67], v37 offset:16384
	ds_read_b128 v[68:71], v37 offset:17408
	ds_read_b128 v[72:75], v37 offset:18432
	ds_read_b128 v[76:79], v37 offset:19456
	v_add_co_u32_e32 v250, vcc, 0xfbc00000, v46
	v_addc_co_u32_e32 v251, vcc, -1, v47, vcc
	v_pk_mul_f32 v[166:167], v[12:13], v[12:13]
	v_pk_mul_f32 v[168:169], v[14:15], v[14:15]
	v_pk_fma_f32 v[166:167], v[8:9], v[8:9], v[166:167]
	v_pk_fma_f32 v[168:169], v[10:11], v[10:11], v[168:169]
	v_pk_fma_f32 v[166:167], v[4:5], v[4:5], v[166:167]
	v_pk_fma_f32 v[168:169], v[6:7], v[6:7], v[168:169]
	v_pk_fma_f32 v[166:167], v[0:1], v[0:1], v[166:167]
	v_pk_fma_f32 v[168:169], v[2:3], v[2:3], v[168:169]
	v_pk_add_f32 v[166:167], v[166:167], v[168:169]
	s_nop 0
	v_add_f32_e32 v164, v166, v167
	v_mov_b32_e32 v165, v164
	s_nop 1
	v_permlane32_swap_b32_e32 v165, v164
	v_add_f32_e32 v164, v164, v165
	v_mov_b32_e32 v165, v164
	s_nop 1
	v_permlane16_swap_b32_e32 v165, v164
	v_add_f32_e32 v164, v164, v165
	s_nop 1
	v_add_f32_dpp v164, v164, v164 row_ror:8 row_mask:0xf bank_mask:0xf
	s_nop 1
	v_add_f32_dpp v164, v164, v164 row_ror:4 row_mask:0xf bank_mask:0xf
	s_nop 1
	v_add_f32_dpp v164, v164, v164 row_ror:2 row_mask:0xf bank_mask:0xf
	s_nop 1
	v_add_f32_dpp v164, v164, v164 row_ror:1 row_mask:0xf bank_mask:0xf
	s_nop 0
	v_fmamk_f32 v164, v164, 0x3a800000, v200
	v_rsq_f32_e32 v164, v164
	s_nop 0
	v_pk_mul_f32 v[12:13], v[12:13], v[164:165] op_sel_hi:[1,0]
	v_pk_mul_f32 v[14:15], v[14:15], v[164:165] op_sel_hi:[1,0]
	v_pk_mul_f32 v[12:13], v[234:235], v[12:13]
	v_pk_mul_f32 v[14:15], v[236:237], v[14:15]
	v_pk_add_f32 v[172:173], v[172:173], 1.0 op_sel_hi:[1,0]
	v_pk_add_f32 v[174:175], v[174:175], 1.0 op_sel_hi:[1,0]
	v_pk_fma_f32 v[12:13], v[172:173], v[12:13], v[80:81]
	v_pk_fma_f32 v[14:15], v[174:175], v[14:15], v[82:83]
	v_cvt_pk_bf16_f32 v12, v12, v13
	v_cvt_pk_bf16_f32 v13, v14, v15
	global_store_dwordx2 v[250:251], v[12:13], off offset:-1536
	ds_read_b128 v[80:83], v37 offset:20480
	v_pk_mul_f32 v[8:9], v[8:9], v[164:165] op_sel_hi:[1,0]
	v_pk_mul_f32 v[10:11], v[10:11], v[164:165] op_sel_hi:[1,0]
	v_pk_mul_f32 v[8:9], v[238:239], v[8:9]
	v_pk_mul_f32 v[10:11], v[240:241], v[10:11]
	v_pk_add_f32 v[176:177], v[176:177], 1.0 op_sel_hi:[1,0]
	v_pk_add_f32 v[178:179], v[178:179], 1.0 op_sel_hi:[1,0]
	v_pk_fma_f32 v[8:9], v[176:177], v[8:9], v[84:85]
	v_pk_fma_f32 v[10:11], v[178:179], v[10:11], v[86:87]
	v_cvt_pk_bf16_f32 v8, v8, v9
	v_cvt_pk_bf16_f32 v9, v10, v11
	global_store_dwordx2 v[250:251], v[8:9], off offset:-1024
	ds_read_b128 v[84:87], v37 offset:21504
	v_pk_mul_f32 v[4:5], v[4:5], v[164:165] op_sel_hi:[1,0]
	v_pk_mul_f32 v[6:7], v[6:7], v[164:165] op_sel_hi:[1,0]
	v_pk_mul_f32 v[4:5], v[242:243], v[4:5]
	v_pk_mul_f32 v[6:7], v[244:245], v[6:7]
	v_pk_add_f32 v[180:181], v[180:181], 1.0 op_sel_hi:[1,0]
	v_pk_add_f32 v[182:183], v[182:183], 1.0 op_sel_hi:[1,0]
	v_pk_fma_f32 v[4:5], v[180:181], v[4:5], v[88:89]
	v_pk_fma_f32 v[6:7], v[182:183], v[6:7], v[90:91]
	v_cvt_pk_bf16_f32 v4, v4, v5
	v_cvt_pk_bf16_f32 v5, v6, v7
	global_store_dwordx2 v[250:251], v[4:5], off offset:-512
	ds_read_b128 v[88:91], v37 offset:22528
	v_pk_mul_f32 v[0:1], v[0:1], v[164:165] op_sel_hi:[1,0]
	v_pk_mul_f32 v[2:3], v[2:3], v[164:165] op_sel_hi:[1,0]
	v_pk_mul_f32 v[0:1], v[246:247], v[0:1]
	v_pk_mul_f32 v[2:3], v[248:249], v[2:3]
	v_pk_add_f32 v[184:185], v[184:185], 1.0 op_sel_hi:[1,0]
	v_pk_add_f32 v[186:187], v[186:187], 1.0 op_sel_hi:[1,0]
	v_pk_fma_f32 v[0:1], v[184:185], v[0:1], v[92:93]
	v_pk_fma_f32 v[2:3], v[186:187], v[2:3], v[94:95]
	v_cvt_pk_bf16_f32 v0, v0, v1
	v_cvt_pk_bf16_f32 v1, v2, v3
	global_store_dwordx2 v[250:251], v[0:1], off
	ds_read_b128 v[92:95], v37 offset:23552
	s_waitcnt vmcnt(8)
	s_mov_b32 s99, 0
	s_add_i32 s72, s13, s48
	s_cmp_gt_i32 s72, 0x87ff
	s_cbranch_scc1 .Lr2_slow_nopf
	s_add_i32 s8, s44, s72
	s_cmp_lt_i32 s8, 0x8800
	s_cbranch_scc0 .Lr2_slow_nopf
	s_mov_b32 s41, s72
	s_mul_hi_i32 s6, s41, 0x78787879
	s_lshr_b32 s7, s6, 31
	s_ashr_i32 s6, s6, 11
	s_add_i32 s6, s6, s7
	s_mul_i32 s7, s6, 0xffffef00
	s_add_i32 s7, s41, s7
	s_cmpk_gt_i32 s7, 0xff
	s_cselect_b64 s[50:51], -1, 0
	s_mul_hi_i32 s9, s8, 0x78787879
	s_lshr_b32 s25, s9, 31
	s_ashr_i32 s9, s9, 11
	s_add_i32 s9, s9, s25
	s_mul_i32 s25, s9, 0xffffef00
	s_add_i32 s25, s8, s25
	s_cmpk_gt_i32 s25, 0xff
	s_cselect_b64 s[52:53], -1, 0
	s_and_b64 s[46:47], s[50:51], s[52:53]
	s_or_b64 s[46:47], s[46:47], s[62:63]
	s_cmp_lg_u64 s[46:47], 0
	s_cbranch_scc0 .Lr2_slow_nopf
; __device__ __forceinline__ float bflo(unsigned w) { return __uint_as_float(w << 16); }
; __device__ __forceinline__ float bfhi(unsigned w) { return __uint_as_float(w & 0xffff0000u); }
;     __device__ __forceinline__ void init(int N, int G, int c, int latent_only) { lat = latent_only; b.init(latent_only ? NB * SEQ : M, N, G, c); }
; __device__ __forceinline__ void row_pass(const RowPass& R, int gw, int ngw, int lane) {
;     ...
;     for (int row0 = gw; row0 < M; row0 += NR * ngw) {
;         f32x4 v[NR][4]; u32x2 yw[NR][4]; bool act[NR]; float* xrow[NR]; int bbs[NR];
; #pragma unroll
;         for (int k = 0; k < NR; ++k) {
;             const int row = row0 + k * ngw;
;             const int rowc = row < M ? row : row0;
;             const int b = rowc / RPB, i = rowc - b * RPB; const bool isctx = i < CTXL;
;             act[k] = (row < M) && !(isctx && R.skip_ctx);
;             bbs[k] = isctx ? 8 : b;
;             xrow[k] = isctx ? R.xc + ((size_t)b * CTXL + i) * DM : R.out + ((size_t)b * SEQ + (i - CTXL)) * DM;
;             const float* src = R.init ? (isctx ? R.ctx_in + ((size_t)b * CTXL + i) * DM : R.x_in + ((size_t)b * SEQ + (i - CTXL)) * DM) : xrow[k];
;             if (act[k]) {
; #pragma unroll
;                 for (int j = 0; j < 4; ++j) v[k][j] = __builtin_nontemporal_load((const f32x4*)(src + lane * 4 + 256 * j));
;                 if (R.update) { const bf16* yr = R.Y + (size_t)rowc * DM;
; #pragma unroll
;                     for (int j = 0; j < 4; ++j) yw[k][j] = __builtin_nontemporal_load((const u32x2*)(yr + lane * 4 + 256 * j)); }
;             }
;     ...
;             if (R.update) {
;                 f32x4 y[4]; float ss = 0.f;
; #pragma unroll
;                 for (int j = 0; j < 4; ++j) { const u32x2 w = yw[k][j]; y[j] = (f32x4){bflo(w.x), bfhi(w.x), bflo(w.y), bfhi(w.y)};
;                     ss += (y[j][0] * y[j][0] + y[j][1] * y[j][1]) + (y[j][2] * y[j][2] + y[j][3] * y[j][3]); }
;                 const float rstd = __builtin_amdgcn_rsqf(wave_sum(ss) * (1.0f / DM) + EPS);
;                 const float* gate = R.mod + ((size_t)(R.lg * 9 + bb) * NMOD + R.gi) * DM;
; #pragma unroll
;                 for (int j = 0; j < 4; ++j) { const f32x4 g = *(const f32x4*)(gate + lane * 4 + 256 * j), gp = *(const f32x4*)(R.gpost + lane * 4 + 256 * j);
;                     v[k][j] = v[k][j] + g * (y[j] * rstd * gp); }
;             }
	s_add_i32 s72, s7, 0xffffff00
	s_cmp_lg_u64 s[50:51], 0
	s_cselect_b32 s27, s4, s49
	s_cselect_b32 s32, s5, s55
	s_cselect_b32 s37, 24, 20
	s_cselect_b32 s72, s72, s7
	s_cselect_b32 s85, s6, 8
	s_mov_b32 s40, s6
	s_mov_b32 s41, 0
	s_lshl_b64 s[40:41], s[40:41], s37
	s_add_u32 s40, s27, s40
	s_addc_u32 s41, s32, s41
	s_lshl_b32 s72, s72, 12
	s_add_u32 s40, s40, s72
	s_addc_u32 s41, s41, 0
	s_add_i32 s27, s85, s3
	s_mul_hi_i32 s32, s27, 0x6000
	s_mulk_i32 s27, 0x6000
	s_add_u32 s66, s34, s27
	s_addc_u32 s67, s35, s32
	s_add_u32 s66, s66, 0x2000
	s_addc_u32 s67, s67, 0
	s_add_i32 s27, s85, s3
	s_mul_hi_i32 s32, s27, 0x6000
	s_mulk_i32 s27, 0x6000
	s_add_u32 s38, s34, s27
	s_addc_u32 s39, s35, s32
	s_add_u32 s38, s38, 0x3000
	s_addc_u32 s39, s39, 0
	s_add_u32 s46, s38, 0x1000
	s_addc_u32 s47, s39, 0
	s_mov_b64 s[6:7], s[52:53]
	s_cmp_lg_u64 s[6:7], 0
	s_cselect_b32 s85, s9, 8
	s_add_i32 s27, s85, s3
	s_mul_hi_i32 s32, s27, 0x6000
	s_mulk_i32 s27, 0x6000
	s_add_u32 s10, s34, s27
	s_addc_u32 s11, s35, s32
	s_add_u32 s10, s10, 0x2000
	s_addc_u32 s11, s11, 0
	s_add_i32 s27, s85, s3
	s_mul_hi_i32 s32, s27, 0x6000
	s_mulk_i32 s27, 0x6000
	s_add_u32 s50, s34, s27
	s_addc_u32 s51, s35, s32
	s_add_u32 s50, s50, 0x3000
	s_addc_u32 s51, s51, 0
	s_add_u32 s52, s50, 0x1000
	s_addc_u32 s53, s51, 0
	s_xor_b32 s25, s93, 0x6000
	v_lshl_add_u64 v[250:251], v[46:47], 0, s[74:75]
	global_load_dwordx4 v[12:15], v160, s[40:41] nt
	global_load_dwordx4 v[8:11], v160, s[40:41] offset:1024 nt
	global_load_dwordx4 v[4:7], v160, s[40:41] offset:2048 nt
	global_load_dwordx4 v[0:3], v160, s[40:41] offset:3072 nt
	global_load_dwordx2 v[54:55], v[250:251], off offset:-1536 nt
	global_load_dwordx2 v[52:53], v[250:251], off offset:-1024 nt
	global_load_dwordx2 v[50:51], v[250:251], off offset:-512 nt
	global_load_dwordx2 v[48:49], v[250:251], off nt
	s_and_b32 s72, s13, 7
	s_and_b32 s85, s72, 3
	s_lshl_b32 s85, s85, 10
	s_lshl_b32 s37, s72, 10
	s_add_i32 s37, s37, s25
	s_cmp_lt_u32 s72, 4
	s_cselect_b32 s6, s66, s38
	s_cselect_b32 s7, s67, s39
	s_cselect_b32 s8, s46, s10
	s_cselect_b32 s9, s47, s11
	s_cselect_b32 s26, s50, s52
	s_cselect_b32 s27, s51, s53
	s_add_u32 s6, s6, s85
	s_addc_u32 s7, s7, 0
	s_add_u32 s8, s8, s85
	s_addc_u32 s9, s9, 0
	s_add_u32 s26, s26, s85
	s_addc_u32 s27, s27, 0
	s_mov_b32 m0, s37
	s_nop 0
	global_load_lds_dwordx4 v160, s[6:7]
	s_add_i32 s37, s37, 0x2000
	s_mov_b32 m0, s37
	s_nop 0
	global_load_lds_dwordx4 v160, s[8:9]
	s_add_i32 s37, s37, 0x2000
	s_mov_b32 m0, s37
	s_nop 0
	global_load_lds_dwordx4 v160, s[26:27]
	s_mov_b32 s99, 1
.Lr2_slow_nopf:
	v_lshlrev_b32_e32 v32, 16, v62
	v_and_b32_e32 v33, 0xffff0000, v62
	v_lshlrev_b32_e32 v34, 16, v63
	v_and_b32_e32 v35, 0xffff0000, v63
	v_pk_mul_f32 v[166:167], v[32:33], v[32:33]
	v_pk_mul_f32 v[168:169], v[34:35], v[34:35]
	v_lshlrev_b32_e32 v32, 16, v60
	v_and_b32_e32 v33, 0xffff0000, v60
	v_lshlrev_b32_e32 v34, 16, v61
	v_and_b32_e32 v35, 0xffff0000, v61
	v_pk_fma_f32 v[166:167], v[32:33], v[32:33], v[166:167]
	v_pk_fma_f32 v[168:169], v[34:35], v[34:35], v[168:169]
	v_lshlrev_b32_e32 v32, 16, v58
	v_and_b32_e32 v33, 0xffff0000, v58
	v_lshlrev_b32_e32 v34, 16, v59
	v_and_b32_e32 v35, 0xffff0000, v59
	v_pk_fma_f32 v[166:167], v[32:33], v[32:33], v[166:167]
	v_pk_fma_f32 v[168:169], v[34:35], v[34:35], v[168:169]
	v_lshlrev_b32_e32 v32, 16, v56
	v_and_b32_e32 v33, 0xffff0000, v56
	v_lshlrev_b32_e32 v34, 16, v57
	v_and_b32_e32 v35, 0xffff0000, v57
	v_pk_fma_f32 v[166:167], v[32:33], v[32:33], v[166:167]
	v_pk_fma_f32 v[168:169], v[34:35], v[34:35], v[168:169]
	v_pk_add_f32 v[166:167], v[166:167], v[168:169]
	s_nop 0
	v_add_f32_e32 v164, v166, v167
	v_mov_b32_e32 v165, v164
	s_nop 1
	v_permlane32_swap_b32_e32 v165, v164
	v_add_f32_e32 v164, v164, v165
	v_mov_b32_e32 v165, v164
	s_nop 1
	v_permlane16_swap_b32_e32 v165, v164
	v_add_f32_e32 v164, v164, v165
	s_nop 1
	v_add_f32_dpp v164, v164, v164 row_ror:8 row_mask:0xf bank_mask:0xf
	s_nop 1
	v_add_f32_dpp v164, v164, v164 row_ror:4 row_mask:0xf bank_mask:0xf
	s_nop 1
	v_add_f32_dpp v164, v164, v164 row_ror:2 row_mask:0xf bank_mask:0xf
	s_nop 1
	v_add_f32_dpp v164, v164, v164 row_ror:1 row_mask:0xf bank_mask:0xf
	s_nop 0
	v_fmamk_f32 v164, v164, 0x3a800000, v200
	v_rsq_f32_e32 v164, v164
	v_lshlrev_b32_e32 v32, 16, v62
	v_and_b32_e32 v33, 0xffff0000, v62
	v_lshlrev_b32_e32 v34, 16, v63
	v_and_b32_e32 v35, 0xffff0000, v63
	v_pk_mul_f32 v[32:33], v[32:33], v[164:165] op_sel_hi:[1,0]
	v_pk_mul_f32 v[34:35], v[34:35], v[164:165] op_sel_hi:[1,0]
	v_pk_mul_f32 v[32:33], v[218:219], v[32:33]
	v_pk_mul_f32 v[34:35], v[220:221], v[34:35]
	s_waitcnt lgkmcnt(11)
	v_pk_fma_f32 v[16:17], v[188:189], v[32:33], v[16:17]
	v_pk_fma_f32 v[18:19], v[190:191], v[34:35], v[18:19]
	global_store_dwordx4 v160, v[16:19], s[64:65] nt
	v_lshlrev_b32_e32 v32, 16, v60
	v_and_b32_e32 v33, 0xffff0000, v60
	v_lshlrev_b32_e32 v34, 16, v61
	v_and_b32_e32 v35, 0xffff0000, v61
	v_pk_mul_f32 v[32:33], v[32:33], v[164:165] op_sel_hi:[1,0]
	v_pk_mul_f32 v[34:35], v[34:35], v[164:165] op_sel_hi:[1,0]
	v_pk_mul_f32 v[32:33], v[222:223], v[32:33]
	v_pk_mul_f32 v[34:35], v[224:225], v[34:35]
	s_waitcnt lgkmcnt(10)
; __device__ __forceinline__ unsigned pk2(float lo, float hi) { return pg8::cvt_pk_bf16(lo, hi); }
;     __device__ __forceinline__ void init(int N, int G, int c, int latent_only) { lat = latent_only; b.init(latent_only ? NB * SEQ : M, N, G, c); }
;     __device__ __forceinline__ void init(int c_, unsigned* cnt_) { lat.init(NB * SEQ, FF2, 1, 0); c = c_; cnt = cnt_; }
; __device__ __forceinline__ void row_pass(const RowPass& R, int gw, int ngw, int lane) {
;     ...
;                 for (int j = 0; j < 4; ++j) { const f32x4 g = *(const f32x4*)(gate + lane * 4 + 256 * j), gp = *(const f32x4*)(R.gpost + lane * 4 + 256 * j);
;                     v[k][j] = v[k][j] + g * (y[j] * rstd * gp); }
;             }
;             if (R.init || R.update) {
; #pragma unroll
;                 for (int j = 0; j < 4; ++j) __builtin_nontemporal_store(v[k][j], (f32x4*)(xrow[k] + lane * 4 + 256 * j));
;             }
;             if (R.norm_out) {
;                 float ss = 0.f;
; #pragma unroll
;                 for (int j = 0; j < 4; ++j) ss += (v[k][j][0] * v[k][j][0] + v[k][j][1] * v[k][j][1]) + (v[k][j][2] * v[k][j][2] + v[k][j][3] * v[k][j][3]);
;                 const float rstd = __builtin_amdgcn_rsqf(wave_sum(ss) * (1.0f / DM) + EPS);
;                 const float* shift = R.mod + ((size_t)(R.ln * 9 + bb) * NMOD + R.si) * DM; const float* scale = shift + DM;
;                 bf16* hr = R.H + (size_t)row * DM;
; #pragma unroll
;                 for (int j = 0; j < 4; ++j) { const f32x4 gp = *(const f32x4*)(R.gpre + lane * 4 + 256 * j), sh = *(const f32x4*)(shift + lane * 4 + 256 * j), sc = *(const f32x4*)(scale + lane * 4 + 256 * j);
;                     const f32x4 hv = (v[k][j] * rstd * gp) * (sc + 1.0f) + sh;
;                     u32x2 w; w.x = pk2(hv[0], hv[1]); w.y = pk2(hv[2], hv[3]); *(u32x2*)(hr + lane * 4 + 256 * j) = w; }
;             }
;         }
	v_pk_fma_f32 v[20:21], v[192:193], v[32:33], v[20:21]
	v_pk_fma_f32 v[22:23], v[194:195], v[34:35], v[22:23]
	global_store_dwordx4 v160, v[20:23], s[64:65] offset:1024 nt
	v_lshlrev_b32_e32 v32, 16, v58
	v_and_b32_e32 v33, 0xffff0000, v58
	v_lshlrev_b32_e32 v34, 16, v59
	v_and_b32_e32 v35, 0xffff0000, v59
	v_pk_mul_f32 v[32:33], v[32:33], v[164:165] op_sel_hi:[1,0]
	v_pk_mul_f32 v[34:35], v[34:35], v[164:165] op_sel_hi:[1,0]
	v_pk_mul_f32 v[32:33], v[226:227], v[32:33]
	v_pk_mul_f32 v[34:35], v[228:229], v[34:35]
	s_waitcnt lgkmcnt(9)
	v_pk_fma_f32 v[24:25], v[196:197], v[32:33], v[24:25]
	v_pk_fma_f32 v[26:27], v[198:199], v[34:35], v[26:27]
	global_store_dwordx4 v160, v[24:27], s[64:65] offset:2048 nt
	v_lshlrev_b32_e32 v32, 16, v56
	v_and_b32_e32 v33, 0xffff0000, v56
	v_lshlrev_b32_e32 v34, 16, v57
	v_and_b32_e32 v35, 0xffff0000, v57
	v_pk_mul_f32 v[32:33], v[32:33], v[164:165] op_sel_hi:[1,0]
	v_pk_mul_f32 v[34:35], v[34:35], v[164:165] op_sel_hi:[1,0]
	v_pk_mul_f32 v[32:33], v[230:231], v[32:33]
	v_pk_mul_f32 v[34:35], v[232:233], v[34:35]
	s_waitcnt lgkmcnt(8)
	v_pk_fma_f32 v[28:29], v[96:97], v[32:33], v[28:29]
	v_pk_fma_f32 v[30:31], v[98:99], v[34:35], v[30:31]
	global_store_dwordx4 v160, v[28:31], s[64:65] offset:3072 nt
	v_pk_mul_f32 v[166:167], v[16:17], v[16:17]
	v_pk_mul_f32 v[168:169], v[18:19], v[18:19]
	v_pk_fma_f32 v[166:167], v[20:21], v[20:21], v[166:167]
	v_pk_fma_f32 v[168:169], v[22:23], v[22:23], v[168:169]
	v_pk_fma_f32 v[166:167], v[24:25], v[24:25], v[166:167]
	v_pk_fma_f32 v[168:169], v[26:27], v[26:27], v[168:169]
	v_pk_fma_f32 v[166:167], v[28:29], v[28:29], v[166:167]
	v_pk_fma_f32 v[168:169], v[30:31], v[30:31], v[168:169]
	v_pk_add_f32 v[166:167], v[166:167], v[168:169]
	s_nop 0
	v_add_f32_e32 v164, v166, v167
	v_mov_b32_e32 v165, v164
	s_nop 1
	v_permlane32_swap_b32_e32 v165, v164
	v_add_f32_e32 v164, v164, v165
	v_mov_b32_e32 v165, v164
	s_nop 1
	v_permlane16_swap_b32_e32 v165, v164
	v_add_f32_e32 v164, v164, v165
	s_nop 1
	v_add_f32_dpp v164, v164, v164 row_ror:8 row_mask:0xf bank_mask:0xf
	s_nop 1
	v_add_f32_dpp v164, v164, v164 row_ror:4 row_mask:0xf bank_mask:0xf
	s_nop 1
	v_add_f32_dpp v164, v164, v164 row_ror:2 row_mask:0xf bank_mask:0xf
	s_nop 1
	v_add_f32_dpp v164, v164, v164 row_ror:1 row_mask:0xf bank_mask:0xf
	s_nop 0
	v_fmamk_f32 v164, v164, 0x3a800000, v200
	v_rsq_f32_e32 v164, v164
	s_nop 0
	v_pk_mul_f32 v[16:17], v[16:17], v[164:165] op_sel_hi:[1,0]
	v_pk_mul_f32 v[18:19], v[18:19], v[164:165] op_sel_hi:[1,0]
	v_pk_mul_f32 v[16:17], v[234:235], v[16:17]
	v_pk_mul_f32 v[18:19], v[236:237], v[18:19]
	s_waitcnt lgkmcnt(3)
	v_pk_add_f32 v[80:81], v[80:81], 1.0 op_sel_hi:[1,0]
	v_pk_add_f32 v[82:83], v[82:83], 1.0 op_sel_hi:[1,0]
	v_pk_fma_f32 v[16:17], v[80:81], v[16:17], v[64:65]
	v_pk_fma_f32 v[18:19], v[82:83], v[18:19], v[66:67]
	v_cvt_pk_bf16_f32 v16, v16, v17
	v_cvt_pk_bf16_f32 v17, v18, v19
	global_store_dwordx2 v[252:253], v[16:17], off
	v_pk_mul_f32 v[20:21], v[20:21], v[164:165] op_sel_hi:[1,0]
	v_pk_mul_f32 v[22:23], v[22:23], v[164:165] op_sel_hi:[1,0]
	v_pk_mul_f32 v[20:21], v[238:239], v[20:21]
	v_pk_mul_f32 v[22:23], v[240:241], v[22:23]
	s_waitcnt lgkmcnt(2)
	v_pk_add_f32 v[84:85], v[84:85], 1.0 op_sel_hi:[1,0]
	v_pk_add_f32 v[86:87], v[86:87], 1.0 op_sel_hi:[1,0]
	v_pk_fma_f32 v[20:21], v[84:85], v[20:21], v[68:69]
	v_pk_fma_f32 v[22:23], v[86:87], v[22:23], v[70:71]
	v_cvt_pk_bf16_f32 v20, v20, v21
	v_cvt_pk_bf16_f32 v21, v22, v23
	global_store_dwordx2 v[252:253], v[20:21], off offset:512
	v_pk_mul_f32 v[24:25], v[24:25], v[164:165] op_sel_hi:[1,0]
	v_pk_mul_f32 v[26:27], v[26:27], v[164:165] op_sel_hi:[1,0]
	v_pk_mul_f32 v[24:25], v[242:243], v[24:25]
	v_pk_mul_f32 v[26:27], v[244:245], v[26:27]
	s_waitcnt lgkmcnt(1)
	v_pk_add_f32 v[88:89], v[88:89], 1.0 op_sel_hi:[1,0]
	v_pk_add_f32 v[90:91], v[90:91], 1.0 op_sel_hi:[1,0]
	v_pk_fma_f32 v[24:25], v[88:89], v[24:25], v[72:73]
	v_pk_fma_f32 v[26:27], v[90:91], v[26:27], v[74:75]
	v_cvt_pk_bf16_f32 v24, v24, v25
	v_cvt_pk_bf16_f32 v25, v26, v27
	global_store_dwordx2 v[252:253], v[24:25], off offset:1024
	v_pk_mul_f32 v[28:29], v[28:29], v[164:165] op_sel_hi:[1,0]
	v_pk_mul_f32 v[30:31], v[30:31], v[164:165] op_sel_hi:[1,0]
	v_pk_mul_f32 v[28:29], v[246:247], v[28:29]
	v_pk_mul_f32 v[30:31], v[248:249], v[30:31]
	s_waitcnt lgkmcnt(0)
	v_pk_add_f32 v[92:93], v[92:93], 1.0 op_sel_hi:[1,0]
	v_pk_add_f32 v[94:95], v[94:95], 1.0 op_sel_hi:[1,0]
	v_pk_fma_f32 v[28:29], v[92:93], v[28:29], v[76:77]
	v_pk_fma_f32 v[30:31], v[94:95], v[30:31], v[78:79]
	v_cvt_pk_bf16_f32 v28, v28, v29
	v_cvt_pk_bf16_f32 v29, v30, v31
	global_store_dwordx2 v[252:253], v[28:29], off offset:1536
	s_xor_b32 s93, s93, 0x6000
	s_branch .LBB0_131

; __device__ __forceinline__ float bflo(unsigned w) { return __uint_as_float(w << 16); }
; __device__ __forceinline__ void row_pass(const RowPass& R, int gw, int ngw, int lane) {
;     constexpr int NR = 2;
;     for (int row0 = gw; row0 < M; row0 += NR * ngw) {
;         f32x4 v[NR][4]; u32x2 yw[NR][4]; bool act[NR]; float* xrow[NR]; int bbs[NR];
; #pragma unroll
;         for (int k = 0; k < NR; ++k) {
;             const int row = row0 + k * ngw;
;             const int rowc = row < M ? row : row0;
;             const int b = rowc / RPB, i = rowc - b * RPB; const bool isctx = i < CTXL;
;             act[k] = (row < M) && !(isctx && R.skip_ctx);
;             bbs[k] = isctx ? 8 : b;
;             xrow[k] = isctx ? R.xc + ((size_t)b * CTXL + i) * DM : R.out + ((size_t)b * SEQ + (i - CTXL)) * DM;
;             const float* src = R.init ? (isctx ? R.ctx_in + ((size_t)b * CTXL + i) * DM : R.x_in + ((size_t)b * SEQ + (i - CTXL)) * DM) : xrow[k];
;             if (act[k]) {
; #pragma unroll
;                 for (int j = 0; j < 4; ++j) v[k][j] = __builtin_nontemporal_load((const f32x4*)(src + lane * 4 + 256 * j));
;                 if (R.update) { const bf16* yr = R.Y + (size_t)rowc * DM;
; #pragma unroll
;                     for (int j = 0; j < 4; ++j) yw[k][j] = __builtin_nontemporal_load((const u32x2*)(yr + lane * 4 + 256 * j)); }
;             }
;         }
; #pragma unroll
;         for (int k = 0; k < NR; ++k) {
;             if (!act[k]) continue;
;             const int row = row0 + k * ngw, bb = bbs[k];
;             if (R.update) {
;                 f32x4 y[4]; float ss = 0.f;
; #pragma unroll
;                 for (int j = 0; j < 4; ++j) { const u32x2 w = yw[k][j]; y[j] = (f32x4){bflo(w.x), bfhi(w.x), bflo(w.y), bfhi(w.y)};
;                     ss += (y[j][0] * y[j][0] + y[j][1] * y[j][1]) + (y[j][2] * y[j][2] + y[j][3] * y[j][3]); }
;                 const float rstd = __builtin_amdgcn_rsqf(wave_sum(ss) * (1.0f / DM) + EPS);
;                 const float* gate = R.mod + ((size_t)(R.lg * 9 + bb) * NMOD + R.gi) * DM;
; #pragma unroll
;                 for (int j = 0; j < 4; ++j) { const f32x4 g = *(const f32x4*)(gate + lane * 4 + 256 * j), gp = *(const f32x4*)(R.gpost + lane * 4 + 256 * j);
;                     v[k][j] = v[k][j] + g * (y[j] * rstd * gp); }
.LBB0_145:
	v_readlane_b32 s6, v255, 17
	v_readlane_b32 s7, v255, 18
	s_and_b64 vcc, exec, s[6:7]
	s_cbranch_vccz .LBB0_160
	s_cmp_gt_i32 s36, 0x87ff
	s_cbranch_scc1 .LBB0_159
	s_sub_i32 s3, s57, 30
	s_cmp_lt_u32 s3, -7
	s_cselect_b64 s[4:5], -1, 0
	s_cmp_lg_u64 s[4:5], 0
	s_load_dwordx2 s[8:9], s[0:1], 0x30
	s_addc_u32 s13, s12, 0
	s_lshl_b32 s6, s13, 10
	s_ashr_i32 s7, s6, 31
	s_lshl_b64 s[6:7], s[6:7], 2
	s_load_dwordx2 s[22:23], s[0:1], 0xa0
	s_load_dwordx2 s[10:11], s[0:1], 0x48
	s_waitcnt lgkmcnt(0)
	s_add_u32 s6, s8, s6
	s_addc_u32 s7, s9, s7
	s_lshl_b32 s8, s12, 10
	s_ashr_i32 s9, s8, 31
	s_lshl_b64 s[8:9], s[8:9], 2
	s_add_u32 s8, s10, s8
	s_addc_u32 s9, s11, s9
	s_waitcnt vmcnt(0)
	v_lshlrev_b32_e32 v0, 4, v216
	v_mov_b32_e32 v1, v161
	s_ashr_i32 s37, s36, 31
	v_lshl_add_u64 v[44:45], s[6:7], 0, v[0:1]
	s_lshl_b64 s[6:7], s[36:37], 11
	s_add_u32 s6, s28, s6
	v_lshlrev_b32_e32 v160, 3, v216
	s_addc_u32 s7, s29, s7
	v_lshl_add_u64 v[42:43], s[8:9], 0, v[0:1]
	v_lshl_add_u64 v[0:1], s[6:7], 0, v[160:161]
	s_mov_b64 s[6:7], 0xa7fa600
	v_lshlrev_b32_e32 v36, 2, v216
	v_lshl_add_u64 v[38:39], s[20:21], 0, v[160:161]
	v_lshl_add_u64 v[40:41], s[60:61], 0, v[160:161]
	s_mul_i32 s3, s12, 9
	s_mul_i32 s13, s13, 9
	v_lshl_add_u64 v[46:47], v[0:1], 0, s[6:7]
	s_mov_b32 s93, 0
	s_mov_b32 s99, 0
	global_load_dwordx4 v[218:221], v[42:43], off
	global_load_dwordx4 v[222:225], v[42:43], off offset:1024
	global_load_dwordx4 v[226:229], v[42:43], off offset:2048
	global_load_dwordx4 v[230:233], v[42:43], off offset:3072
	global_load_dwordx4 v[234:237], v[44:45], off
	global_load_dwordx4 v[238:241], v[44:45], off offset:1024
	global_load_dwordx4 v[242:245], v[44:45], off offset:2048
	global_load_dwordx4 v[246:249], v[44:45], off offset:3072
	s_mov_b32 s19, s36
	s_branch .LBB0_149

;     __device__ __forceinline__ void init(int N, int G, int c, int latent_only) { lat = latent_only; b.init(latent_only ? NB * SEQ : M, N, G, c); }
;     __device__ __forceinline__ void init(int c_, unsigned* cnt_) { lat.init(NB * SEQ, FF2, 1, 0); c = c_; cnt = cnt_; }
; __device__ __forceinline__ void row_pass(const RowPass& R, int gw, int ngw, int lane) {
;     ...
;     for (int row0 = gw; row0 < M; row0 += NR * ngw) {
;         f32x4 v[NR][4]; u32x2 yw[NR][4]; bool act[NR]; float* xrow[NR]; int bbs[NR];
; #pragma unroll
;         for (int k = 0; k < NR; ++k) {
;             const int row = row0 + k * ngw;
;             const int rowc = row < M ? row : row0;
;             const int b = rowc / RPB, i = rowc - b * RPB; const bool isctx = i < CTXL;
;             act[k] = (row < M) && !(isctx && R.skip_ctx);
;             bbs[k] = isctx ? 8 : b;
;             xrow[k] = isctx ? R.xc + ((size_t)b * CTXL + i) * DM : R.out + ((size_t)b * SEQ + (i - CTXL)) * DM;
;             const float* src = R.init ? (isctx ? R.ctx_in + ((size_t)b * CTXL + i) * DM : R.x_in + ((size_t)b * SEQ + (i - CTXL)) * DM) : xrow[k];
;             if (act[k]) {
; #pragma unroll
;                 for (int j = 0; j < 4; ++j) v[k][j] = __builtin_nontemporal_load((const f32x4*)(src + lane * 4 + 256 * j));
;                 if (R.update) { const bf16* yr = R.Y + (size_t)rowc * DM;
; #pragma unroll
;                     for (int j = 0; j < 4; ++j) yw[k][j] = __builtin_nontemporal_load((const u32x2*)(yr + lane * 4 + 256 * j)); }
;             }
.LBB0_149:
	s_mul_hi_i32 s6, s19, 0x78787879
	s_lshr_b32 s7, s6, 31
	s_ashr_i32 s6, s6, 11
	s_add_i32 s6, s6, s7
	s_mul_i32 s7, s6, 0xffffef00
	s_add_i32 s7, s19, s7
	s_cmpk_gt_i32 s7, 0xff
	s_cselect_b64 s[50:51], -1, 0
	s_add_i32 s8, s44, s19
	s_cmp_lt_i32 s8, 0x8800
	s_cbranch_scc0 .Lr3_slow
	s_mul_hi_i32 s9, s8, 0x78787879
	s_lshr_b32 s25, s9, 31
	s_ashr_i32 s9, s9, 11
	s_add_i32 s9, s9, s25
	s_mul_i32 s25, s9, 0xffffef00
	s_add_i32 s25, s8, s25
	s_cmpk_gt_i32 s25, 0xff
	s_cselect_b64 s[52:53], -1, 0
	s_cmp_lg_u64 s[4:5], 0
	s_cbranch_scc0 .Lr3_slow_u
	v_lshlrev_b32_e32 v160, 2, v36
	s_add_i32 s72, s7, 0xffffff00
	s_cmp_lg_u64 s[50:51], 0
	s_cselect_b32 s27, s22, s49
	s_cselect_b32 s32, s23, s55
	s_cselect_b32 s37, 24, 20
	s_cselect_b32 s72, s72, s7
	s_cselect_b32 s85, s6, 8
	s_mov_b32 s40, s6
	s_mov_b32 s41, 0
	s_lshl_b64 s[40:41], s[40:41], s37
	s_add_u32 s40, s27, s40
	s_addc_u32 s41, s32, s41
	s_lshl_b32 s72, s72, 12
	s_add_u32 s40, s40, s72
	s_addc_u32 s41, s41, 0
	s_add_i32 s27, s85, s3
	s_mul_hi_i32 s32, s27, 0x6000
	s_mulk_i32 s27, 0x6000
	s_add_u32 s66, s34, s27
	s_addc_u32 s67, s35, s32
	s_add_u32 s66, s66, 0x5000
	s_addc_u32 s67, s67, 0
	s_add_i32 s27, s85, s13
	s_mul_hi_i32 s32, s27, 0x6000
	s_mulk_i32 s27, 0x6000
	s_add_u32 s38, s34, s27
	s_addc_u32 s39, s35, s32
	s_add_u32 s46, s38, 0x1000
	s_addc_u32 s47, s39, 0
	s_mov_b32 s6, s8
	s_ashr_i32 s7, s8, 31
	s_lshl_b64 s[6:7], s[6:7], 11
	v_lshl_add_u64 v[250:251], v[38:39], 0, s[6:7]
	v_lshl_add_u64 v[252:253], v[40:41], 0, s[6:7]
	s_mov_b64 s[6:7], s[52:53]
	s_add_i32 s72, s25, 0xffffff00
	s_cmp_lg_u64 s[6:7], 0
	s_cselect_b32 s27, s22, s49
	s_cselect_b32 s32, s23, s55
	s_cselect_b32 s37, 24, 20
	s_cselect_b32 s72, s72, s25
	s_cselect_b32 s85, s9, 8
	s_mov_b32 s64, s9
	s_mov_b32 s65, 0
	s_lshl_b64 s[64:65], s[64:65], s37
	s_add_u32 s64, s27, s64
	s_addc_u32 s65, s32, s65
	s_lshl_b32 s72, s72, 12
	s_add_u32 s64, s64, s72
	s_addc_u32 s65, s65, 0
	s_add_i32 s27, s85, s3
	s_mul_hi_i32 s32, s27, 0x6000
	s_mulk_i32 s27, 0x6000
	s_add_u32 s10, s34, s27
	s_addc_u32 s11, s35, s32
	s_add_u32 s10, s10, 0x5000
	s_addc_u32 s11, s11, 0
	s_add_i32 s27, s85, s13
	s_mul_hi_i32 s32, s27, 0x6000
	s_mulk_i32 s27, 0x6000
	s_add_u32 s50, s34, s27
	s_addc_u32 s51, s35, s32
	s_add_u32 s52, s50, 0x1000
	s_addc_u32 s53, s51, 0
	s_cmp_lg_u32 s99, 0
	s_cbranch_scc1 .Lr3_slow_pf
	global_load_dwordx4 v[12:15], v160, s[40:41] nt
	global_load_dwordx4 v[8:11], v160, s[40:41] offset:1024 nt
	global_load_dwordx4 v[4:7], v160, s[40:41] offset:2048 nt
	global_load_dwordx4 v[0:3], v160, s[40:41] offset:3072 nt
	global_load_dwordx2 v[54:55], v[46:47], off offset:-1536 nt
	global_load_dwordx2 v[52:53], v[46:47], off offset:-1024 nt
	global_load_dwordx2 v[50:51], v[46:47], off offset:-512 nt
	global_load_dwordx2 v[48:49], v[46:47], off nt
	s_and_b32 s72, s19, 7
	s_and_b32 s85, s72, 3
	s_lshl_b32 s85, s85, 10
	s_lshl_b32 s37, s72, 10
	s_add_i32 s37, s37, s93
	s_cmp_lt_u32 s72, 4
	s_cselect_b32 s6, s66, s38
	s_cselect_b32 s7, s67, s39
	s_cselect_b32 s8, s46, s10
	s_cselect_b32 s9, s47, s11
	s_cselect_b32 s26, s50, s52
	s_cselect_b32 s27, s51, s53
	s_add_u32 s6, s6, s85
	s_addc_u32 s7, s7, 0
	s_add_u32 s8, s8, s85
	s_addc_u32 s9, s9, 0
	s_add_u32 s26, s26, s85
	s_addc_u32 s27, s27, 0
	s_mov_b32 m0, s37
	s_nop 0
	global_load_lds_dwordx4 v160, s[6:7]
	s_add_i32 s37, s37, 0x2000
	s_mov_b32 m0, s37
	s_nop 0
	global_load_lds_dwordx4 v160, s[8:9]
	s_add_i32 s37, s37, 0x2000
	s_mov_b32 m0, s37
	s_nop 0
	global_load_lds_dwordx4 v160, s[26:27]
	global_load_dwordx4 v[16:19], v160, s[64:65] nt
	global_load_dwordx4 v[20:23], v160, s[64:65] offset:1024 nt
	global_load_dwordx4 v[24:27], v160, s[64:65] offset:2048 nt
	global_load_dwordx4 v[28:31], v160, s[64:65] offset:3072 nt
	global_load_dwordx2 v[62:63], v[250:251], off nt
	global_load_dwordx2 v[60:61], v[250:251], off offset:512 nt
	global_load_dwordx2 v[58:59], v[250:251], off offset:1024 nt
	global_load_dwordx2 v[56:57], v[250:251], off offset:1536 nt
	s_waitcnt vmcnt(8)
	s_branch .Lr3_slow_proc

; __device__ __forceinline__ float bflo(unsigned w) { return __uint_as_float(w << 16); }
; __device__ __forceinline__ float bfhi(unsigned w) { return __uint_as_float(w & 0xffff0000u); }
;     __device__ __forceinline__ void init(int N, int G, int c, int latent_only) { lat = latent_only; b.init(latent_only ? NB * SEQ : M, N, G, c); }
;     __device__ __forceinline__ void init(int c_, unsigned* cnt_) { lat.init(NB * SEQ, FF2, 1, 0); c = c_; cnt = cnt_; }
; __device__ __forceinline__ void row_pass(const RowPass& R, int gw, int ngw, int lane) {
;     ...
;             if (R.update) {
;                 f32x4 y[4]; float ss = 0.f;
; #pragma unroll
;                 for (int j = 0; j < 4; ++j) { const u32x2 w = yw[k][j]; y[j] = (f32x4){bflo(w.x), bfhi(w.x), bflo(w.y), bfhi(w.y)};
;                     ss += (y[j][0] * y[j][0] + y[j][1] * y[j][1]) + (y[j][2] * y[j][2] + y[j][3] * y[j][3]); }
;                 const float rstd = __builtin_amdgcn_rsqf(wave_sum(ss) * (1.0f / DM) + EPS);
;                 const float* gate = R.mod + ((size_t)(R.lg * 9 + bb) * NMOD + R.gi) * DM;
; #pragma unroll
;                 for (int j = 0; j < 4; ++j) { const f32x4 g = *(const f32x4*)(gate + lane * 4 + 256 * j), gp = *(const f32x4*)(R.gpost + lane * 4 + 256 * j);
;                     v[k][j] = v[k][j] + g * (y[j] * rstd * gp); }
;             }
;             if (R.init || R.update) {
; #pragma unroll
;                 for (int j = 0; j < 4; ++j) __builtin_nontemporal_store(v[k][j], (f32x4*)(xrow[k] + lane * 4 + 256 * j));
;             }
.Lr3_slow_proc:
	s_barrier
	v_add_u32_e32 v37, s93, v160
	ds_read_b128 v[64:67], v37
	ds_read_b128 v[68:71], v37 offset:1024
	ds_read_b128 v[72:75], v37 offset:2048
	ds_read_b128 v[76:79], v37 offset:3072
	ds_read_b128 v[80:83], v37 offset:4096
	ds_read_b128 v[84:87], v37 offset:5120
	ds_read_b128 v[88:91], v37 offset:6144
	ds_read_b128 v[92:95], v37 offset:7168
	ds_read_b128 v[172:175], v37 offset:8192
	ds_read_b128 v[176:179], v37 offset:9216
	ds_read_b128 v[180:183], v37 offset:10240
	ds_read_b128 v[184:187], v37 offset:11264
	v_lshlrev_b32_e32 v32, 16, v54
	v_and_b32_e32 v33, 0xffff0000, v54
	v_lshlrev_b32_e32 v34, 16, v55
	v_and_b32_e32 v35, 0xffff0000, v55
	v_pk_mul_f32 v[166:167], v[32:33], v[32:33]
	v_pk_mul_f32 v[168:169], v[34:35], v[34:35]
	v_lshlrev_b32_e32 v32, 16, v52
	v_and_b32_e32 v33, 0xffff0000, v52
	v_lshlrev_b32_e32 v34, 16, v53
	v_and_b32_e32 v35, 0xffff0000, v53
	v_pk_fma_f32 v[166:167], v[32:33], v[32:33], v[166:167]
	v_pk_fma_f32 v[168:169], v[34:35], v[34:35], v[168:169]
	v_lshlrev_b32_e32 v32, 16, v50
	v_and_b32_e32 v33, 0xffff0000, v50
	v_lshlrev_b32_e32 v34, 16, v51
	v_and_b32_e32 v35, 0xffff0000, v51
	v_pk_fma_f32 v[166:167], v[32:33], v[32:33], v[166:167]
	v_pk_fma_f32 v[168:169], v[34:35], v[34:35], v[168:169]
	v_lshlrev_b32_e32 v32, 16, v48
	v_and_b32_e32 v33, 0xffff0000, v48
	v_lshlrev_b32_e32 v34, 16, v49
	v_and_b32_e32 v35, 0xffff0000, v49
	v_pk_fma_f32 v[166:167], v[32:33], v[32:33], v[166:167]
	v_pk_fma_f32 v[168:169], v[34:35], v[34:35], v[168:169]
	v_pk_add_f32 v[166:167], v[166:167], v[168:169]
	s_nop 0
	v_add_f32_e32 v164, v166, v167
	v_mov_b32_e32 v165, v164
	s_nop 1
	v_permlane32_swap_b32_e32 v165, v164
	v_add_f32_e32 v164, v164, v165
	v_mov_b32_e32 v165, v164
	s_nop 1
	v_permlane16_swap_b32_e32 v165, v164
	v_add_f32_e32 v164, v164, v165
	s_nop 1
	v_add_f32_dpp v164, v164, v164 row_ror:8 row_mask:0xf bank_mask:0xf
	s_nop 1
	v_add_f32_dpp v164, v164, v164 row_ror:4 row_mask:0xf bank_mask:0xf
	s_nop 1
	v_add_f32_dpp v164, v164, v164 row_ror:2 row_mask:0xf bank_mask:0xf
	s_nop 1
	v_add_f32_dpp v164, v164, v164 row_ror:1 row_mask:0xf bank_mask:0xf
	s_nop 0
	v_fmamk_f32 v164, v164, 0x3a800000, v200
	v_rsq_f32_e32 v164, v164
	v_lshlrev_b32_e32 v32, 16, v54
	v_and_b32_e32 v33, 0xffff0000, v54
	v_lshlrev_b32_e32 v34, 16, v55
	v_and_b32_e32 v35, 0xffff0000, v55
	v_pk_mul_f32 v[32:33], v[32:33], v[164:165] op_sel_hi:[1,0]
	v_pk_mul_f32 v[34:35], v[34:35], v[164:165] op_sel_hi:[1,0]
	v_pk_mul_f32 v[32:33], v[218:219], v[32:33]
	v_pk_mul_f32 v[34:35], v[220:221], v[34:35]
	s_waitcnt lgkmcnt(11)
	v_pk_fma_f32 v[12:13], v[64:65], v[32:33], v[12:13]
	v_pk_fma_f32 v[14:15], v[66:67], v[34:35], v[14:15]
	global_store_dwordx4 v160, v[12:15], s[40:41] nt
	v_lshlrev_b32_e32 v32, 16, v52
	v_and_b32_e32 v33, 0xffff0000, v52
	v_lshlrev_b32_e32 v34, 16, v53
	v_and_b32_e32 v35, 0xffff0000, v53
	v_pk_mul_f32 v[32:33], v[32:33], v[164:165] op_sel_hi:[1,0]
	v_pk_mul_f32 v[34:35], v[34:35], v[164:165] op_sel_hi:[1,0]
	v_pk_mul_f32 v[32:33], v[222:223], v[32:33]
	v_pk_mul_f32 v[34:35], v[224:225], v[34:35]
	s_waitcnt lgkmcnt(10)
	v_pk_fma_f32 v[8:9], v[68:69], v[32:33], v[8:9]
	v_pk_fma_f32 v[10:11], v[70:71], v[34:35], v[10:11]
	global_store_dwordx4 v160, v[8:11], s[40:41] offset:1024 nt
	v_lshlrev_b32_e32 v32, 16, v50
	v_and_b32_e32 v33, 0xffff0000, v50
	v_lshlrev_b32_e32 v34, 16, v51
	v_and_b32_e32 v35, 0xffff0000, v51
	v_pk_mul_f32 v[32:33], v[32:33], v[164:165] op_sel_hi:[1,0]
	v_pk_mul_f32 v[34:35], v[34:35], v[164:165] op_sel_hi:[1,0]
	v_pk_mul_f32 v[32:33], v[226:227], v[32:33]
	v_pk_mul_f32 v[34:35], v[228:229], v[34:35]
	s_waitcnt lgkmcnt(9)
	v_pk_fma_f32 v[4:5], v[72:73], v[32:33], v[4:5]
	v_pk_fma_f32 v[6:7], v[74:75], v[34:35], v[6:7]
	global_store_dwordx4 v160, v[4:7], s[40:41] offset:2048 nt
	v_lshlrev_b32_e32 v32, 16, v48
	v_and_b32_e32 v33, 0xffff0000, v48
	v_lshlrev_b32_e32 v34, 16, v49
	v_and_b32_e32 v35, 0xffff0000, v49
	v_pk_mul_f32 v[32:33], v[32:33], v[164:165] op_sel_hi:[1,0]
	v_pk_mul_f32 v[34:35], v[34:35], v[164:165] op_sel_hi:[1,0]
	v_pk_mul_f32 v[32:33], v[230:231], v[32:33]
	v_pk_mul_f32 v[34:35], v[232:233], v[34:35]
	s_waitcnt lgkmcnt(8)
	v_pk_fma_f32 v[0:1], v[76:77], v[32:33], v[0:1]
	v_pk_fma_f32 v[2:3], v[78:79], v[34:35], v[2:3]
	global_store_dwordx4 v160, v[0:3], s[40:41] offset:3072 nt
	s_waitcnt lgkmcnt(0)
; __device__ __forceinline__ unsigned pk2(float lo, float hi) { return pg8::cvt_pk_bf16(lo, hi); }
; __device__ __forceinline__ void row_pass(const RowPass& R, int gw, int ngw, int lane) {
;     ...
;     for (int row0 = gw; row0 < M; row0 += NR * ngw) {
;         f32x4 v[NR][4]; u32x2 yw[NR][4]; bool act[NR]; float* xrow[NR]; int bbs[NR];
; #pragma unroll
;         for (int k = 0; k < NR; ++k) {
;             const int row = row0 + k * ngw;
;             const int rowc = row < M ? row : row0;
;             const int b = rowc / RPB, i = rowc - b * RPB; const bool isctx = i < CTXL;
;             act[k] = (row < M) && !(isctx && R.skip_ctx);
;             bbs[k] = isctx ? 8 : b;
;             xrow[k] = isctx ? R.xc + ((size_t)b * CTXL + i) * DM : R.out + ((size_t)b * SEQ + (i - CTXL)) * DM;
;             const float* src = R.init ? (isctx ? R.ctx_in + ((size_t)b * CTXL + i) * DM : R.x_in + ((size_t)b * SEQ + (i - CTXL)) * DM) : xrow[k];
;             if (act[k]) {
; #pragma unroll
;                 for (int j = 0; j < 4; ++j) v[k][j] = __builtin_nontemporal_load((const f32x4*)(src + lane * 4 + 256 * j));
;                 if (R.update) { const bf16* yr = R.Y + (size_t)rowc * DM;
; #pragma unroll
;                     for (int j = 0; j < 4; ++j) yw[k][j] = __builtin_nontemporal_load((const u32x2*)(yr + lane * 4 + 256 * j)); }
;             }
;     ...
;             if (R.norm_out) {
;                 float ss = 0.f;
; #pragma unroll
;                 for (int j = 0; j < 4; ++j) ss += (v[k][j][0] * v[k][j][0] + v[k][j][1] * v[k][j][1]) + (v[k][j][2] * v[k][j][2] + v[k][j][3] * v[k][j][3]);
;                 const float rstd = __builtin_amdgcn_rsqf(wave_sum(ss) * (1.0f / DM) + EPS);
;                 const float* shift = R.mod + ((size_t)(R.ln * 9 + bb) * NMOD + R.si) * DM; const float* scale = shift + DM;
;                 bf16* hr = R.H + (size_t)row * DM;
; #pragma unroll
;                 for (int j = 0; j < 4; ++j) { const f32x4 gp = *(const f32x4*)(R.gpre + lane * 4 + 256 * j), sh = *(const f32x4*)(shift + lane * 4 + 256 * j), sc = *(const f32x4*)(scale + lane * 4 + 256 * j);
;                     const f32x4 hv = (v[k][j] * rstd * gp) * (sc + 1.0f) + sh;
;                     u32x2 w; w.x = pk2(hv[0], hv[1]); w.y = pk2(hv[2], hv[3]); *(u32x2*)(hr + lane * 4 + 256 * j) = w; }
;             }
	ds_read_b128 v[188:191], v37 offset:12288
	ds_read_b128 v[192:195], v37 offset:13312
	ds_read_b128 v[196:199], v37 offset:14336
	ds_read_b128 v[96:99], v37 offset:15360
	ds_read_b128 v[64:67], v37 offset:16384
	ds_read_b128 v[68:71], v37 offset:17408
	ds_read_b128 v[72:75], v37 offset:18432
	ds_read_b128 v[76:79], v37 offset:19456
	v_add_co_u32_e32 v250, vcc, 0xfbc00000, v46
	v_addc_co_u32_e32 v251, vcc, -1, v47, vcc
	v_pk_mul_f32 v[166:167], v[12:13], v[12:13]
	v_pk_mul_f32 v[168:169], v[14:15], v[14:15]
	v_pk_fma_f32 v[166:167], v[8:9], v[8:9], v[166:167]
	v_pk_fma_f32 v[168:169], v[10:11], v[10:11], v[168:169]
	v_pk_fma_f32 v[166:167], v[4:5], v[4:5], v[166:167]
	v_pk_fma_f32 v[168:169], v[6:7], v[6:7], v[168:169]
	v_pk_fma_f32 v[166:167], v[0:1], v[0:1], v[166:167]
	v_pk_fma_f32 v[168:169], v[2:3], v[2:3], v[168:169]
	v_pk_add_f32 v[166:167], v[166:167], v[168:169]
	s_nop 0
	v_add_f32_e32 v164, v166, v167
	v_mov_b32_e32 v165, v164
	s_nop 1
	v_permlane32_swap_b32_e32 v165, v164
	v_add_f32_e32 v164, v164, v165
	v_mov_b32_e32 v165, v164
	s_nop 1
	v_permlane16_swap_b32_e32 v165, v164
	v_add_f32_e32 v164, v164, v165
	s_nop 1
	v_add_f32_dpp v164, v164, v164 row_ror:8 row_mask:0xf bank_mask:0xf
	s_nop 1
	v_add_f32_dpp v164, v164, v164 row_ror:4 row_mask:0xf bank_mask:0xf
	s_nop 1
	v_add_f32_dpp v164, v164, v164 row_ror:2 row_mask:0xf bank_mask:0xf
	s_nop 1
	v_add_f32_dpp v164, v164, v164 row_ror:1 row_mask:0xf bank_mask:0xf
	s_nop 0
	v_fmamk_f32 v164, v164, 0x3a800000, v200
	v_rsq_f32_e32 v164, v164
	s_nop 0
	v_pk_mul_f32 v[12:13], v[12:13], v[164:165] op_sel_hi:[1,0]
	v_pk_mul_f32 v[14:15], v[14:15], v[164:165] op_sel_hi:[1,0]
	v_pk_mul_f32 v[12:13], v[234:235], v[12:13]
	v_pk_mul_f32 v[14:15], v[236:237], v[14:15]
	v_pk_add_f32 v[172:173], v[172:173], 1.0 op_sel_hi:[1,0]
	v_pk_add_f32 v[174:175], v[174:175], 1.0 op_sel_hi:[1,0]
	v_pk_fma_f32 v[12:13], v[172:173], v[12:13], v[80:81]
	v_pk_fma_f32 v[14:15], v[174:175], v[14:15], v[82:83]
	v_cvt_pk_bf16_f32 v12, v12, v13
	v_cvt_pk_bf16_f32 v13, v14, v15
	global_store_dwordx2 v[250:251], v[12:13], off offset:-1536
	ds_read_b128 v[80:83], v37 offset:20480
	v_pk_mul_f32 v[8:9], v[8:9], v[164:165] op_sel_hi:[1,0]
	v_pk_mul_f32 v[10:11], v[10:11], v[164:165] op_sel_hi:[1,0]
	v_pk_mul_f32 v[8:9], v[238:239], v[8:9]
	v_pk_mul_f32 v[10:11], v[240:241], v[10:11]
	v_pk_add_f32 v[176:177], v[176:177], 1.0 op_sel_hi:[1,0]
	v_pk_add_f32 v[178:179], v[178:179], 1.0 op_sel_hi:[1,0]
	v_pk_fma_f32 v[8:9], v[176:177], v[8:9], v[84:85]
	v_pk_fma_f32 v[10:11], v[178:179], v[10:11], v[86:87]
	v_cvt_pk_bf16_f32 v8, v8, v9
	v_cvt_pk_bf16_f32 v9, v10, v11
	global_store_dwordx2 v[250:251], v[8:9], off offset:-1024
	ds_read_b128 v[84:87], v37 offset:21504
	v_pk_mul_f32 v[4:5], v[4:5], v[164:165] op_sel_hi:[1,0]
	v_pk_mul_f32 v[6:7], v[6:7], v[164:165] op_sel_hi:[1,0]
	v_pk_mul_f32 v[4:5], v[242:243], v[4:5]
	v_pk_mul_f32 v[6:7], v[244:245], v[6:7]
	v_pk_add_f32 v[180:181], v[180:181], 1.0 op_sel_hi:[1,0]
	v_pk_add_f32 v[182:183], v[182:183], 1.0 op_sel_hi:[1,0]
	v_pk_fma_f32 v[4:5], v[180:181], v[4:5], v[88:89]
	v_pk_fma_f32 v[6:7], v[182:183], v[6:7], v[90:91]
	v_cvt_pk_bf16_f32 v4, v4, v5
	v_cvt_pk_bf16_f32 v5, v6, v7
	global_store_dwordx2 v[250:251], v[4:5], off offset:-512
	ds_read_b128 v[88:91], v37 offset:22528
	v_pk_mul_f32 v[0:1], v[0:1], v[164:165] op_sel_hi:[1,0]
	v_pk_mul_f32 v[2:3], v[2:3], v[164:165] op_sel_hi:[1,0]
	v_pk_mul_f32 v[0:1], v[246:247], v[0:1]
	v_pk_mul_f32 v[2:3], v[248:249], v[2:3]
	v_pk_add_f32 v[184:185], v[184:185], 1.0 op_sel_hi:[1,0]
	v_pk_add_f32 v[186:187], v[186:187], 1.0 op_sel_hi:[1,0]
	v_pk_fma_f32 v[0:1], v[184:185], v[0:1], v[92:93]
	v_pk_fma_f32 v[2:3], v[186:187], v[2:3], v[94:95]
	v_cvt_pk_bf16_f32 v0, v0, v1
	v_cvt_pk_bf16_f32 v1, v2, v3
	global_store_dwordx2 v[250:251], v[0:1], off
	ds_read_b128 v[92:95], v37 offset:23552
	s_waitcnt vmcnt(8)
	s_mov_b32 s99, 0
	s_add_i32 s72, s19, s48
	s_cmp_gt_i32 s72, 0x87ff
	s_cbranch_scc1 .Lr3_slow_nopf
	s_add_i32 s8, s44, s72
	s_cmp_lt_i32 s8, 0x8800
	s_cbranch_scc0 .Lr3_slow_nopf
	s_mov_b32 s41, s72
	s_mul_hi_i32 s6, s41, 0x78787879
	s_lshr_b32 s7, s6, 31
	s_ashr_i32 s6, s6, 11
	s_add_i32 s6, s6, s7
	s_mul_i32 s7, s6, 0xffffef00
	s_add_i32 s7, s41, s7
	s_cmpk_gt_i32 s7, 0xff
	s_cselect_b64 s[50:51], -1, 0
	s_mul_hi_i32 s9, s8, 0x78787879
	s_lshr_b32 s25, s9, 31
	s_ashr_i32 s9, s9, 11
	s_add_i32 s9, s9, s25
	s_mul_i32 s25, s9, 0xffffef00
	s_add_i32 s25, s8, s25
	s_cmpk_gt_i32 s25, 0xff
	s_cselect_b64 s[52:53], -1, 0
	s_cmp_lg_u64 s[4:5], 0
	s_cbranch_scc0 .Lr3_slow_nopf
	s_add_i32 s72, s7, 0xffffff00
	s_cmp_lg_u64 s[50:51], 0
	s_cselect_b32 s27, s22, s49
	s_cselect_b32 s32, s23, s55
	s_cselect_b32 s37, 24, 20
	s_cselect_b32 s72, s72, s7
	s_cselect_b32 s85, s6, 8
	s_mov_b32 s40, s6
	s_mov_b32 s41, 0
	s_lshl_b64 s[40:41], s[40:41], s37
	s_add_u32 s40, s27, s40
	s_addc_u32 s41, s32, s41
	s_lshl_b32 s72, s72, 12
	s_add_u32 s40, s40, s72
	s_addc_u32 s41, s41, 0
	s_add_i32 s27, s85, s3
	s_mul_hi_i32 s32, s27, 0x6000
	s_mulk_i32 s27, 0x6000
	s_add_u32 s66, s34, s27
	s_addc_u32 s67, s35, s32
	s_add_u32 s66, s66, 0x5000
	s_addc_u32 s67, s67, 0
	s_add_i32 s27, s85, s13
	s_mul_hi_i32 s32, s27, 0x6000
	s_mulk_i32 s27, 0x6000
	s_add_u32 s38, s34, s27
	s_addc_u32 s39, s35, s32
	s_add_u32 s46, s38, 0x1000
	s_addc_u32 s47, s39, 0
	s_mov_b64 s[6:7], s[52:53]
	s_cmp_lg_u64 s[6:7], 0
	s_cselect_b32 s85, s9, 8
	s_add_i32 s27, s85, s3
	s_mul_hi_i32 s32, s27, 0x6000
	s_mulk_i32 s27, 0x6000
	s_add_u32 s10, s34, s27
	s_addc_u32 s11, s35, s32
	s_add_u32 s10, s10, 0x5000
	s_addc_u32 s11, s11, 0
	s_add_i32 s27, s85, s13
	s_mul_hi_i32 s32, s27, 0x6000
	s_mulk_i32 s27, 0x6000
	s_add_u32 s50, s34, s27
	s_addc_u32 s51, s35, s32
	s_add_u32 s52, s50, 0x1000
	s_addc_u32 s53, s51, 0
	s_xor_b32 s25, s93, 0x6000
	v_lshl_add_u64 v[250:251], v[46:47], 0, s[74:75]
	global_load_dwordx4 v[12:15], v160, s[40:41] nt
	global_load_dwordx4 v[8:11], v160, s[40:41] offset:1024 nt
	global_load_dwordx4 v[4:7], v160, s[40:41] offset:2048 nt
	global_load_dwordx4 v[0:3], v160, s[40:41] offset:3072 nt
	global_load_dwordx2 v[54:55], v[250:251], off offset:-1536 nt
	global_load_dwordx2 v[52:53], v[250:251], off offset:-1024 nt
	global_load_dwordx2 v[50:51], v[250:251], off offset:-512 nt
	global_load_dwordx2 v[48:49], v[250:251], off nt
	s_and_b32 s72, s19, 7
	s_and_b32 s85, s72, 3
	s_lshl_b32 s85, s85, 10
	s_lshl_b32 s37, s72, 10
	s_add_i32 s37, s37, s25
	s_cmp_lt_u32 s72, 4
	s_cselect_b32 s6, s66, s38
	s_cselect_b32 s7, s67, s39
	s_cselect_b32 s8, s46, s10
	s_cselect_b32 s9, s47, s11
	s_cselect_b32 s26, s50, s52
	s_cselect_b32 s27, s51, s53
	s_add_u32 s6, s6, s85
	s_addc_u32 s7, s7, 0
	s_add_u32 s8, s8, s85
	s_addc_u32 s9, s9, 0
	s_add_u32 s26, s26, s85
	s_addc_u32 s27, s27, 0
	s_mov_b32 m0, s37
	s_nop 0
	global_load_lds_dwordx4 v160, s[6:7]
	s_add_i32 s37, s37, 0x2000
	s_mov_b32 m0, s37
	s_nop 0
	global_load_lds_dwordx4 v160, s[8:9]
	s_add_i32 s37, s37, 0x2000
	s_mov_b32 m0, s37
	s_nop 0
	global_load_lds_dwordx4 v160, s[26:27]
	s_mov_b32 s99, 1
